# grid barrier: XCD leader publishes the per-XCD generation before its own L1 invalidate (both still waited), on top of v11
# baseline (speedup 1.0000x reference)
.LBB0_454:
	s_or_b64 exec, exec, s[6:7]
	v_mov_b32_e32 v0, s1
	v_add_co_u32_e32 v0, vcc, 0x2000, v0
	v_mov_b32_e32 v1, s0
	s_nop 0
	v_addc_co_u32_e32 v1, vcc, 0, v1, vcc
	v_mov_b32_e32 v2, 1
	s_waitcnt vmcnt(0) lgkmcnt(0)
	flat_atomic_add v[0:1], v2 offset:1024
	buffer_inv sc1
	s_waitcnt vmcnt(0)

.LBB0_458:
	s_or_b64 exec, exec, s[6:7]
	v_mov_b32_e32 v0, s1
	v_add_co_u32_e32 v0, vcc, 0x2000, v0
	v_mov_b32_e32 v1, s0
	s_nop 0
	v_addc_co_u32_e32 v1, vcc, 0, v1, vcc
	s_waitcnt vmcnt(0) lgkmcnt(0)
	flat_atomic_add v[0:1], v253 offset:1024
	buffer_inv sc1
	s_waitcnt vmcnt(0)

.LBB0_1134:
	s_or_b64 exec, exec, s[8:9]
	v_mov_b32_e32 v0, s1
	v_add_co_u32_e32 v0, vcc, 0x2000, v0
	v_mov_b32_e32 v1, s0
	s_nop 0
	v_addc_co_u32_e32 v1, vcc, 0, v1, vcc
	s_waitcnt vmcnt(0) lgkmcnt(0)
	flat_atomic_add v[0:1], v253 offset:1024
	buffer_inv sc1
	s_waitcnt vmcnt(0)
